# prompt-scan loop: vector-memory issue balanced over the four barrier segments (W1/B'/U0 tile loads of each stage issued one segment earlier into dedicated landing registers, 4/3/4/3 instead of 1/6/1/6
# baseline (speedup 1.0000x reference)
; __device__ __forceinline__ void seq_item(const Params& p, unsigned char* shm, int row0, int nchunks, int h, const float* S0, float* Sout) {
;     ...
;     auto gload = [&](int ci, Stage& G) {
;         const size_t cb = (size_t)(chi0 + ci * 16) * 4096 + crow * 64 + cseg;
;         G.g[0] = *(const u32x4*)(p.W1G + cb); G.g[1] = *(const u32x4*)(p.BPG + cb); G.g[2] = *(const u32x4*)(p.U0G + cb); G.g[3] = *(const u32x4*)(p.VKG + cb);
;         G.gc = *(const f32x4*)(p.GCG + (size_t)(chi0 + ci * 16) * 64 + (tid & 15) * 4);
;     };
;     auto park = [&](int slot, const Stage& G) {
;         bf16_t* d = ring + slot * SLOT;
; #pragma unroll
;         for (int a = 0; a < 4; ++a) *(u32x4*)(d + a * 64 * LD + crow * LD + cseg) = G.g[a];
;         if (tid < 16) *(f32x4*)((float*)(d + 4 * 64 * LD) + tid * 4) = G.gc;
;     };
;     auto body = [&](int ci, int slot, int pslot, const Stage& G) {
;         const bf16_t* W1s = ring + slot * SLOT; const bf16_t* BPs = W1s + 64 * LD; const bf16_t* U0s = BPs + 64 * LD; const bf16_t* VKs = U0s + 64 * LD;
;         const float* GCs = (const float*)(VKs + 64 * LD);
;         const size_t cb = (size_t)(chi0 + ci * 16) * 4096;
; #pragma unroll
;         for (int q = 0; q < 2; ++q) *(u32x2*)(Sb + (16 * (nv0 + q) + fr) * LD + c0) = pk_bf4(S[q]);
;         LDS_BARRIER();
;         park(pslot, G);
;         *(u32x4*)(p.Z + (size_t)(row0 + ci * 64 + crow) * LDZ + ZC_S + h * 64 + cseg) = *(const u32x4*)(Sb + crow * LD + cseg);
;         const bf16x8 w10 = ldfrag(W1s, LD, 16 * m, 0, fr, fq), w11 = ldfrag(W1s, LD, 16 * m, 32, fr, fq);
; #pragma unroll
;         for (int q = 0; q < 2; ++q) {
;             const int v = 16 * (nv0 + q) + fr;
;             f32x4 acc = up_bf4(*(const u32x2*)(U0s + v * LD + c0));
;             acc = MFMA16(w10, ldfrag(Sb, LD, 16 * (nv0 + q), 0, fr, fq), acc);
;             acc = MFMA16(w11, ldfrag(Sb, LD, 16 * (nv0 + q), 32, fr, fq), acc);
;             *(u32x2*)(UT + v * LD + c0) = pk_bf4(acc);
;         }
;         LDS_BARRIER();
;         *(u32x4*)(p.UTG + cb + crow * 64 + cseg) = *(const u32x4*)(UT + crow * LD + cseg);
;         const bf16x8 bp0 = ldfrag(BPs, LD, 16 * m, 0, fr, fq), bp1 = ldfrag(BPs, LD, 16 * m, 32, fr, fq);
;         const f32x4 gc = *(const f32x4*)(GCs + c0);
; #pragma unroll
;         for (int q = 0; q < 2; ++q) {
;             const int v = 16 * (nv0 + q) + fr;
.LBB0_434:
	s_or_b64 exec, exec, s[4:5]
	s_add_i32 s4, 0, 0x12100
	s_waitcnt vmcnt(4)
	ds_write_b128 v60, v[4:7] offset:55552
	s_waitcnt vmcnt(3)
	ds_write_b128 v60, v[12:15] offset:64768
	v_add3_u32 v4, s4, v51, v48
	s_add_i32 s4, 0, 0x14500
	s_waitcnt vmcnt(2)
	ds_write_b128 v4, v[8:11]
	v_add3_u32 v4, s4, v51, v48
	s_waitcnt vmcnt(0)
	ds_write_b128 v4, v[16:19]
	s_and_saveexec_b64 s[4:5], s[8:9]
	v_add_u32_e32 v4, 0x16900, v23
	ds_write_b128 v4, v[0:3]
	s_or_b64 exec, exec, s[4:5]
	s_or_b32 s4, s6, 32
	s_ashr_i32 s5, s4, 31
	s_lshl_b64 s[24:25], s[4:5], 12
	v_lshl_add_u64 v[0:1], s[24:25], 0, v[20:21]
	v_or_b32_e32 v0, v0, v22
	s_lshl_b64 s[4:5], s[4:5], 8
	v_lshlrev_b64 v[12:13], 1, v[0:1]
	s_add_u32 s4, s10, s4
	v_lshl_add_u64 v[0:1], s[12:13], 0, v[12:13]
	v_lshl_add_u64 v[4:5], s[14:15], 0, v[12:13]
	v_lshl_add_u64 v[8:9], s[16:17], 0, v[12:13]
	v_lshl_add_u64 v[12:13], s[18:19], 0, v[12:13]
	s_addc_u32 s5, s11, s5
	global_load_dwordx4 v[220:223], v[0:1], off
	v_and_b32_e32 v61, 2, v169
	global_load_dwordx4 v[224:227], v[4:5], off
	v_or_b32_e32 v52, v20, v22
	global_load_dwordx4 v[228:231], v[8:9], off
	v_lshl_or_b32 v20, v61, 4, v161
	global_load_dwordx4 v[12:15], v[12:13], off
	v_bfe_u32 v21, v133, 4, 2
	global_load_dwordx4 v[16:19], v120, s[4:5]
	v_and_b32_e32 v23, 0x70, v164
	v_mul_u32_u24_e32 v62, 0x48, v20
	v_lshl_or_b32 v50, v21, 2, v23
	v_lshl_add_u32 v20, v62, 1, 0
	v_lshlrev_b32_e32 v22, 1, v50
	v_add_u32_e32 v24, 0x900, v20
	v_add_u32_e32 v63, v20, v22
	v_add_u32_e32 v64, v24, v22
	v_or_b32_e32 v22, v23, v161
	v_mov_b32_e32 v49, 0
	v_mul_u32_u24_e32 v65, 0x90, v22
	v_lshlrev_b32_e32 v22, 3, v21
	v_lshlrev_b32_e32 v21, 4, v21
	v_add_u32_e32 v66, v20, v21
	v_add_u32_e32 v67, v24, v21
	s_or_b32 s24, s6, 48
	s_or_b32 s25, s6, 64
	s_lshl_b64 s[6:7], s[6:7], 13
	v_and_b32_e32 v20, 0x3f80, v166
	v_mov_b32_e32 v21, v49
	v_lshl_add_u64 v[56:57], s[6:7], 0, v[20:21]
	s_add_i32 s6, s21, s20
	s_add_i32 s6, s6, 16
	s_ashr_i32 s7, s6, 31
	v_and_b32_e32 v23, 7, v133
	s_lshl_b64 s[6:7], s[6:7], 13
	s_mov_b32 s5, 0
	v_mov_b32_e32 v121, v49
	s_lshl_b32 s4, s20, 6
	v_lshlrev_b32_e32 v23, 4, v23
	v_lshl_add_u64 v[58:59], s[6:7], 0, v[20:21]
	s_mov_b32 s22, 2
	v_mov_b32_e32 v53, v49
	v_lshl_add_u64 v[54:55], s[10:11], 0, v[120:121]
	v_add_u32_e32 v68, s23, v164
	v_or_b32_e32 v56, v56, v23
	v_or_b32_e32 v58, v58, v23
	s_mov_b32 s26, -2
	s_movk_i32 s27, 0x3a00
	s_lshl_b32 s4, s4, 1
	s_mov_b64 s[6:7], 0x40000
	v_lshlrev_b32_e32 v69, 1, v22
	s_mov_b32 s28, s5
	v_mov_b32_e32 v20, v49
	v_mov_b32_e32 v22, v49
	v_mov_b32_e32 v23, v49
	v_mov_b32_e32 v24, v49
	v_mov_b32_e32 v25, v49
	v_mov_b32_e32 v26, v49
	v_mov_b32_e32 v27, v49
	s_mov_b32 s86, 0
	s_lshl_b32 s86, s86, 4
	s_add_i32 s86, s24, s86
	s_ashr_i32 s87, s86, 31
	s_lshl_b64 s[88:89], s[86:87], 12
	v_lshl_add_u64 v[190:191], s[88:89], 0, v[52:53]
	v_lshlrev_b64 v[190:191], 1, v[190:191]
	v_lshl_add_u64 v[192:193], s[12:13], 0, v[190:191]
	global_load_dwordx4 v[200:203], v[192:193], off
	v_lshl_add_u64 v[194:195], s[14:15], 0, v[190:191]
	global_load_dwordx4 v[204:207], v[194:195], off
	v_lshl_add_u64 v[192:193], s[16:17], 0, v[190:191]
	global_load_dwordx4 v[208:211], v[192:193], off
	s_waitcnt vmcnt(0)
	s_branch .LBB0_438
.LBB0_437:
	s_or_b64 exec, exec, s[22:23]
	s_add_i32 s22, s28, 1
	s_cmp_lg_u32 s28, 2
	s_cselect_b32 s22, s22, 0
	s_mul_i32 s23, s22, 0x9100
	s_add_i32 s23, s23, 0
	v_add3_u32 v80, s23, v65, v69
	v_add3_u32 v81, s23, v70, v71
	ds_read_b64 v[38:39], v81 offset:36864
	s_waitcnt vmcnt(7)
	ds_read_b128 v[28:31], v80 offset:18496
	ds_read_b128 v[32:35], v80 offset:18432
	ds_read_b128 v[40:43], v60
	ds_read_b128 v[44:47], v66
	ds_read_b128 v[70:73], v66 offset:64
	ds_read_b128 v[74:77], v67 offset:64
	s_waitcnt lgkmcnt(6)
	v_lshlrev_b32_e32 v36, 16, v38
	v_and_b32_e32 v37, 0xffff0000, v38
	v_lshlrev_b32_e32 v38, 16, v39
	v_and_b32_e32 v39, 0xffff0000, v39
	v_add_u32_e32 v82, 64, v68
	v_mov_b64_e32 v[78:79], s[20:21]
	s_waitcnt lgkmcnt(2)
	v_mfma_f32_16x16x32_bf16 v[36:39], v[32:35], v[44:47], v[36:39]
	ds_read_b128 v[44:47], v67
	v_mad_i64_i32 v[78:79], s[20:21], v82, s27, v[78:79]
	s_waitcnt lgkmcnt(2)
	v_mfma_f32_16x16x32_bf16 v[36:39], v[28:31], v[70:73], v[36:39]
	v_add_u32_e32 v68, 0x80, v68
	v_lshl_add_u64 v[56:57], v[56:57], 0, s[6:7]
	s_add_i32 s86, s26, 2
	s_min_u32 s86, s86, 0x7c
	s_lshl_b32 s86, s86, 4
	s_add_i32 s86, s24, s86
	s_ashr_i32 s87, s86, 31
	s_lshl_b64 s[88:89], s[86:87], 12
	v_lshl_add_u64 v[190:191], s[88:89], 0, v[52:53]
	v_lshlrev_b64 v[190:191], 1, v[190:191]
	v_lshl_add_u64 v[192:193], s[12:13], 0, v[190:191]
	global_load_dwordx4 v[200:203], v[192:193], off
	v_lshl_add_u64 v[194:195], s[14:15], 0, v[190:191]
	global_load_dwordx4 v[204:207], v[194:195], off
	v_lshl_add_u64 v[192:193], s[16:17], 0, v[190:191]
	global_load_dwordx4 v[208:211], v[192:193], off
	s_nop 5
	v_cvt_pk_bf16_f32 v36, v36, v37
	v_cvt_pk_bf16_f32 v37, v38, v39
	ds_write_b64 v63, v[36:37] offset:9216
	ds_read_b64 v[38:39], v81 offset:39168
	v_lshl_add_u64 v[36:37], v[78:79], 0, s[4:5]
	v_lshl_add_u64 v[70:71], v[36:37], 0, v[48:49]
	v_add_co_u32_e32 v70, vcc, 0x1000, v70
	s_waitcnt lgkmcnt(0)
	v_lshlrev_b32_e32 v36, 16, v38
	v_and_b32_e32 v37, 0xffff0000, v38
	v_lshlrev_b32_e32 v38, 16, v39
	v_and_b32_e32 v39, 0xffff0000, v39
	v_addc_co_u32_e32 v71, vcc, 0, v71, vcc
	s_nop 0
	v_mfma_f32_16x16x32_bf16 v[32:35], v[32:35], v[44:47], v[36:39]
	global_store_dwordx4 v[70:71], v[40:43], off offset:2048
	v_mfma_f32_16x16x32_bf16 v[28:31], v[28:31], v[74:77], v[32:35]
	s_nop 0
	v_lshl_add_u32 v36, v50, 2, s23
	s_nop 5
	v_cvt_pk_bf16_f32 v28, v28, v29
	v_cvt_pk_bf16_f32 v29, v30, v31
	ds_write_b64 v64, v[28:29] offset:9216
	s_waitcnt lgkmcnt(0)
	s_barrier
; #define LDS_BARRIER() do { asm volatile("s_waitcnt lgkmcnt(0)" ::: "memory"); __builtin_amdgcn_s_barrier(); asm volatile("" ::: "memory"); } while (0)
; #define MFMA16(a, b, c) __builtin_amdgcn_mfma_f32_16x16x32_bf16(a, b, c, 0, 0, 0)
; __device__ __forceinline__ f32x4 up_bf4(u32x2 u) { return (f32x4){bf_lo(u.x), bf_hi(u.x), bf_lo(u.y), bf_hi(u.y)}; }
; __device__ __forceinline__ u32x2 pk_bf4(f32x4 v) { u32x2 u; u.x = pk_bf16(v[0], v[1]); u.y = pk_bf16(v[2], v[3]); return u; }
; __device__ __forceinline__ void seq_item(const Params& p, unsigned char* shm, int row0, int nchunks, int h, const float* S0, float* Sout) {
;     ...
;         for (int q = 0; q < 2; ++q) *(u32x2*)(Sb + (16 * (nv0 + q) + fr) * LD + c0) = pk_bf4(S[q]);
;         LDS_BARRIER();
;         park(pslot, G);
;         *(u32x4*)(p.Z + (size_t)(row0 + ci * 64 + crow) * LDZ + ZC_S + h * 64 + cseg) = *(const u32x4*)(Sb + crow * LD + cseg);
;         const bf16x8 w10 = ldfrag(W1s, LD, 16 * m, 0, fr, fq), w11 = ldfrag(W1s, LD, 16 * m, 32, fr, fq);
; #pragma unroll
;         for (int q = 0; q < 2; ++q) {
;             const int v = 16 * (nv0 + q) + fr;
;             f32x4 acc = up_bf4(*(const u32x2*)(U0s + v * LD + c0));
;             acc = MFMA16(w10, ldfrag(Sb, LD, 16 * (nv0 + q), 0, fr, fq), acc);
;             acc = MFMA16(w11, ldfrag(Sb, LD, 16 * (nv0 + q), 32, fr, fq), acc);
;             *(u32x2*)(UT + v * LD + c0) = pk_bf4(acc);
;         }
;         LDS_BARRIER();
;         *(u32x4*)(p.UTG + cb + crow * 64 + cseg) = *(const u32x4*)(UT + crow * LD + cseg);
;         const bf16x8 bp0 = ldfrag(BPs, LD, 16 * m, 0, fr, fq), bp1 = ldfrag(BPs, LD, 16 * m, 32, fr, fq);
;         const f32x4 gc = *(const f32x4*)(GCs + c0);
; #pragma unroll
;         for (int q = 0; q < 2; ++q) {
;             const int v = 16 * (nv0 + q) + fr;
;             f32x4 acc = S[q] * gc + up_bf4(*(const u32x2*)(VKs + v * LD + c0));
;             acc = MFMA16(bp0, ldfrag(UT, LD, 16 * (nv0 + q), 0, fr, fq), acc);
;             acc = MFMA16(bp1, ldfrag(UT, LD, 16 * (nv0 + q), 32, fr, fq), acc);
;             S[q] = acc;
;         }
;     };
;     Stage A, B;
;     gload(0, A); gload(min(1, last), B);
;     park(0, A); park(1, B);
;     gload(min(2, last), A);
;     int scur = 0, spark = 2;
;     for (int ci = 0; ci < nchunks; ci += 2) {
;         gload(min(ci + 3, last), B);
	ds_read_b64 v[40:41], v81 offset:46080
	ds_read_b128 v[28:31], v80 offset:27712
	ds_read_b128 v[32:35], v80 offset:27648
	ds_read_b128 v[36:39], v36 offset:55296
	s_waitcnt lgkmcnt(3)
	v_lshlrev_b32_e32 v44, 16, v40
	v_and_b32_e32 v45, 0xffff0000, v40
	v_lshlrev_b32_e32 v46, 16, v41
	v_and_b32_e32 v47, 0xffff0000, v41
	ds_read_b128 v[40:43], v66 offset:9216
	ds_read_b64 v[74:75], v81 offset:48384
	s_waitcnt lgkmcnt(2)
	v_pk_fma_f32 v[26:27], v[26:27], v[38:39], v[46:47]
	v_pk_fma_f32 v[24:25], v[24:25], v[36:37], v[44:45]
	ds_read_b128 v[44:47], v67 offset:9280
	s_waitcnt lgkmcnt(2)
	v_mfma_f32_16x16x32_bf16 v[24:27], v[32:35], v[40:43], v[24:27]
	ds_read_b128 v[40:43], v66 offset:9280
	ds_read_b128 v[70:73], v67 offset:9216
	s_waitcnt lgkmcnt(1)
	v_mfma_f32_16x16x32_bf16 v[24:27], v[28:31], v[40:43], v[24:27]
	v_lshlrev_b32_e32 v40, 16, v74
	v_and_b32_e32 v41, 0xffff0000, v74
	v_lshlrev_b32_e32 v42, 16, v75
	v_and_b32_e32 v43, 0xffff0000, v75
	v_pk_fma_f32 v[22:23], v[22:23], v[38:39], v[42:43]
	v_pk_fma_f32 v[20:21], v[20:21], v[36:37], v[40:41]
	v_lshl_add_u64 v[36:37], s[10:11], 0, v[58:59]
	s_add_i32 s10, s22, 1
	s_waitcnt lgkmcnt(0)
	v_mfma_f32_16x16x32_bf16 v[20:23], v[32:35], v[70:73], v[20:23]
	ds_read_b128 v[32:35], v60 offset:9216
	s_cmp_lg_u32 s22, 2
	s_cselect_b32 s28, s10, 0
	v_mfma_f32_16x16x32_bf16 v[20:23], v[28:31], v[44:47], v[20:23]
	s_add_i32 s10, s29, 1
	s_cmp_lg_u32 s29, 2
	s_cselect_b32 s22, s10, 0
	s_cmpk_lt_u32 s26, 0x7e
	v_lshl_add_u64 v[58:59], v[58:59], 0, s[6:7]
	s_waitcnt lgkmcnt(0)
	global_store_dwordx4 v[36:37], v[32:35], off
	s_cbranch_scc0 .LBB0_442
.LBB0_438:
	s_add_i32 s26, s26, 2
	s_min_u32 s10, s26, 0x7c
	s_lshl_b32 s10, s10, 4
	s_add_i32 s10, s24, s10
	s_ashr_i32 s11, s10, 31
	s_lshl_b64 s[20:21], s[10:11], 12
	v_lshl_add_u64 v[28:29], s[20:21], 0, v[52:53]
	v_lshlrev_b64 v[28:29], 1, v[28:29]
	v_lshl_add_u64 v[30:31], s[12:13], 0, v[28:29]
	s_nop 0
	v_lshl_add_u64 v[30:31], s[14:15], 0, v[28:29]
	s_nop 0
	v_lshl_add_u64 v[30:31], s[16:17], 0, v[28:29]
	v_lshl_add_u64 v[28:29], s[18:19], 0, v[28:29]
	s_lshl_b64 s[10:11], s[10:11], 8
	global_load_dwordx4 v[44:47], v[28:29], off
	v_lshl_add_u64 v[28:29], v[54:55], 0, s[10:11]
	s_nop 0
	v_cvt_pk_bf16_f32 v70, v24, v25
	global_load_dwordx4 v[28:31], v[28:29], off
	v_cvt_pk_bf16_f32 v71, v26, v27
	ds_write_b64 v63, v[70:71]
	v_cvt_pk_bf16_f32 v70, v20, v21
	v_cvt_pk_bf16_f32 v71, v22, v23
	ds_write_b64 v64, v[70:71]
	s_waitcnt lgkmcnt(0)
	s_barrier
	s_mul_i32 s10, s22, 0x9100
	s_add_i32 s20, s10, 0
	v_add3_u32 v70, s20, v51, v48
	s_waitcnt vmcnt(13)
	ds_write_b128 v70, v[220:223] offset:18432
	s_waitcnt vmcnt(12)
	ds_write_b128 v70, v[224:227] offset:27648
	s_waitcnt vmcnt(11)
	ds_write_b128 v70, v[228:231] offset:36864
	s_waitcnt vmcnt(7)
	ds_write_b128 v70, v[12:15] offset:46080
	s_and_saveexec_b64 s[10:11], s[8:9]
	s_cbranch_execz .LBB0_440
	v_lshl_add_u32 v0, v134, 2, s20
	s_waitcnt vmcnt(7)
	ds_write_b128 v0, v[16:19] offset:55296
; #define LDS_BARRIER() do { asm volatile("s_waitcnt lgkmcnt(0)" ::: "memory"); __builtin_amdgcn_s_barrier(); asm volatile("" ::: "memory"); } while (0)
; __device__ __forceinline__ void seq_item(const Params& p, unsigned char* shm, int row0, int nchunks, int h, const float* S0, float* Sout) {
;     ...
;         for (int q = 0; q < 2; ++q) *(u32x2*)(Sb + (16 * (nv0 + q) + fr) * LD + c0) = pk_bf4(S[q]);
;         LDS_BARRIER();
;         park(pslot, G);
;         *(u32x4*)(p.Z + (size_t)(row0 + ci * 64 + crow) * LDZ + ZC_S + h * 64 + cseg) = *(const u32x4*)(Sb + crow * LD + cseg);
;         const bf16x8 w10 = ldfrag(W1s, LD, 16 * m, 0, fr, fq), w11 = ldfrag(W1s, LD, 16 * m, 32, fr, fq);
; #pragma unroll
;         for (int q = 0; q < 2; ++q) {
;             const int v = 16 * (nv0 + q) + fr;
;             f32x4 acc = up_bf4(*(const u32x2*)(U0s + v * LD + c0));
;             acc = MFMA16(w10, ldfrag(Sb, LD, 16 * (nv0 + q), 0, fr, fq), acc);
;             acc = MFMA16(w11, ldfrag(Sb, LD, 16 * (nv0 + q), 32, fr, fq), acc);
;             *(u32x2*)(UT + v * LD + c0) = pk_bf4(acc);
;         }
;         LDS_BARRIER();
;         *(u32x4*)(p.UTG + cb + crow * 64 + cseg) = *(const u32x4*)(UT + crow * LD + cseg);
;         const bf16x8 bp0 = ldfrag(BPs, LD, 16 * m, 0, fr, fq), bp1 = ldfrag(BPs, LD, 16 * m, 32, fr, fq);
;         const f32x4 gc = *(const f32x4*)(GCs + c0);
; #pragma unroll
;         for (int q = 0; q < 2; ++q) {
;             const int v = 16 * (nv0 + q) + fr;
;             f32x4 acc = S[q] * gc + up_bf4(*(const u32x2*)(VKs + v * LD + c0));
;             acc = MFMA16(bp0, ldfrag(UT, LD, 16 * (nv0 + q), 0, fr, fq), acc);
;             acc = MFMA16(bp1, ldfrag(UT, LD, 16 * (nv0 + q), 32, fr, fq), acc);
;             S[q] = acc;
;         }
;     };
;     Stage A, B;
;     gload(0, A); gload(min(1, last), B);
;     park(0, A); park(1, B);
;     gload(min(2, last), A);
;     int scur = 0, spark = 2;
;     for (int ci = 0; ci < nchunks; ci += 2) {
;         gload(min(ci + 3, last), B);
;         body(ci, scur, spark, A);
;         scur = scur == 2 ? 0 : scur + 1; spark = spark == 2 ? 0 : spark + 1;
;         if (ci + 1 >= nchunks) break;
;         gload(min(ci + 4, last), A);
;         body(ci + 1, scur, spark, B);
;         scur = scur == 2 ? 0 : scur + 1; spark = spark == 2 ? 0 : spark + 1;
;     }
.LBB0_440:
	s_or_b64 exec, exec, s[10:11]
	s_mul_i32 s10, s28, 0x9100
	s_add_i32 s34, s10, 0
	v_lshlrev_b32_e32 v70, 1, v62
	v_lshlrev_b32_e32 v71, 1, v50
	v_add3_u32 v90, s34, v70, v71
	ds_read_b64 v[10:11], v90 offset:36864
	v_add3_u32 v80, s34, v65, v69
	s_mov_b64 s[20:21], s[90:91]
	ds_read_b128 v[0:3], v80 offset:18432
	ds_read_b128 v[4:7], v80 offset:18496
	ds_read_b128 v[12:15], v60
	s_nop 0
	ds_read_b128 v[16:19], v66
	s_waitcnt lgkmcnt(0)
	v_lshlrev_b32_e32 v8, 16, v10
	v_and_b32_e32 v9, 0xffff0000, v10
	v_lshlrev_b32_e32 v10, 16, v11
	v_and_b32_e32 v11, 0xffff0000, v11
	ds_read_b128 v[72:75], v66 offset:64
	v_mov_b64_e32 v[76:77], s[20:21]
	v_mfma_f32_16x16x32_bf16 v[8:11], v[0:3], v[16:19], v[8:11]
	ds_read_b128 v[16:19], v67
	v_mad_i64_i32 v[76:77], s[10:11], v68, s27, v[76:77]
	s_waitcnt lgkmcnt(1)
	v_mfma_f32_16x16x32_bf16 v[8:11], v[4:7], v[72:75], v[8:11]
	s_add_i32 s23, s22, 1
	s_cmp_lg_u32 s22, 2
	s_cselect_b32 s29, s23, 0
	s_min_u32 s22, s26, 0x7b
	s_lshl_b32 s22, s22, 4
	s_min_u32 s86, s26, 0x7b
	s_lshl_b32 s86, s86, 4
	s_add_i32 s86, s25, s86
	s_ashr_i32 s87, s86, 31
	s_lshl_b64 s[88:89], s[86:87], 12
	v_lshl_add_u64 v[190:191], s[88:89], 0, v[52:53]
	v_lshlrev_b64 v[190:191], 1, v[190:191]
	v_lshl_add_u64 v[192:193], s[12:13], 0, v[190:191]
	global_load_dwordx4 v[220:223], v[192:193], off
	v_lshl_add_u64 v[194:195], s[14:15], 0, v[190:191]
	global_load_dwordx4 v[224:227], v[194:195], off
	v_lshl_add_u64 v[192:193], s[16:17], 0, v[190:191]
	global_load_dwordx4 v[228:231], v[192:193], off
	s_nop 2
	v_cvt_pk_bf16_f32 v8, v8, v9
	v_cvt_pk_bf16_f32 v9, v10, v11
	ds_write_b64 v63, v[8:9] offset:9216
	ds_read_b64 v[10:11], v90 offset:39168
	v_lshl_add_u64 v[8:9], v[76:77], 0, s[4:5]
	v_lshl_add_u64 v[72:73], v[8:9], 0, v[48:49]
	v_add_co_u32_e32 v72, vcc, 0x1000, v72
	s_waitcnt lgkmcnt(0)
	v_lshlrev_b32_e32 v8, 16, v10
	v_and_b32_e32 v9, 0xffff0000, v10
	v_lshlrev_b32_e32 v10, 16, v11
	v_and_b32_e32 v11, 0xffff0000, v11
	v_addc_co_u32_e32 v73, vcc, 0, v73, vcc
	s_nop 0
	v_mfma_f32_16x16x32_bf16 v[0:3], v[0:3], v[16:19], v[8:11]
	global_store_dwordx4 v[72:73], v[12:15], off offset:2048
	s_add_i32 s22, s25, s22
	s_ashr_i32 s23, s22, 31
	ds_read_b128 v[8:11], v67 offset:64
	s_waitcnt lgkmcnt(0)
	v_mfma_f32_16x16x32_bf16 v[0:3], v[4:7], v[8:11], v[0:3]
	s_lshl_b64 s[30:31], s[22:23], 12
	s_lshl_b64 s[22:23], s[22:23], 8
	v_lshl_add_u64 v[16:17], v[54:55], 0, s[22:23]
	s_nop 4
	v_cvt_pk_bf16_f32 v0, v0, v1
	v_cvt_pk_bf16_f32 v1, v2, v3
	ds_write_b64 v64, v[0:1] offset:9216
	s_waitcnt lgkmcnt(0)
	s_barrier
	s_mov_b64 s[10:11], s[92:93]
	ds_read_b128 v[0:3], v60 offset:9216
	ds_read_b128 v[72:75], v66 offset:9216
	v_lshl_add_u32 v84, v50, 2, s34
	s_mul_i32 s22, s29, 0x9100
	s_waitcnt lgkmcnt(0)
	v_lshl_add_u64 v[4:5], s[10:11], 0, v[56:57]
	global_store_dwordx4 v[4:5], v[0:3], off
	global_load_dwordx4 v[16:19], v[16:17], off
	s_nop 0
	v_lshl_add_u64 v[0:1], s[30:31], 0, v[52:53]
	v_lshlrev_b64 v[12:13], 1, v[0:1]
	v_lshl_add_u64 v[0:1], s[12:13], 0, v[12:13]
	v_lshl_add_u64 v[4:5], s[14:15], 0, v[12:13]
	v_lshl_add_u64 v[8:9], s[16:17], 0, v[12:13]
	v_lshl_add_u64 v[12:13], s[18:19], 0, v[12:13]
	s_nop 0
	s_add_i32 s30, s22, 0
	s_nop 0
	s_nop 0
	s_nop 0
	s_nop 0
	global_load_dwordx4 v[12:15], v[12:13], off
	ds_read_b64 v[88:89], v90 offset:46080
	ds_read_b128 v[76:79], v80 offset:27648
	ds_read_b128 v[80:83], v80 offset:27712
	ds_read_b128 v[84:87], v84 offset:55296
	ds_read_b64 v[92:93], v90 offset:48384
	s_waitcnt lgkmcnt(4)
	v_lshlrev_b32_e32 v90, 16, v88
	v_and_b32_e32 v91, 0xffff0000, v88
	v_lshlrev_b32_e32 v88, 16, v89
	v_and_b32_e32 v89, 0xffff0000, v89
	s_waitcnt lgkmcnt(1)
	v_pk_fma_f32 v[26:27], v[26:27], v[86:87], v[88:89]
	v_pk_fma_f32 v[24:25], v[24:25], v[84:85], v[90:91]
	s_nop 1
	v_mfma_f32_16x16x32_bf16 v[24:27], v[76:79], v[72:75], v[24:27]
	ds_read_b128 v[72:75], v66 offset:9280
	ds_read_b128 v[88:91], v67 offset:9216
	s_waitcnt lgkmcnt(1)
	v_mfma_f32_16x16x32_bf16 v[24:27], v[80:83], v[72:75], v[24:27]
	v_lshlrev_b32_e32 v72, 16, v92
	v_and_b32_e32 v73, 0xffff0000, v92
	v_lshlrev_b32_e32 v74, 16, v93
	v_and_b32_e32 v75, 0xffff0000, v93
	v_pk_fma_f32 v[22:23], v[22:23], v[86:87], v[74:75]
	v_pk_fma_f32 v[20:21], v[20:21], v[84:85], v[72:73]
	ds_read_b128 v[72:75], v67 offset:9280
	s_waitcnt lgkmcnt(1)
	v_mfma_f32_16x16x32_bf16 v[20:23], v[76:79], v[88:91], v[20:23]
	s_waitcnt lgkmcnt(0)
	v_mfma_f32_16x16x32_bf16 v[20:23], v[80:83], v[72:75], v[20:23]
	v_cvt_pk_bf16_f32 v72, v24, v25
	v_cvt_pk_bf16_f32 v73, v26, v27
	ds_write_b64 v63, v[72:73]
	s_nop 4
	v_cvt_pk_bf16_f32 v72, v20, v21
	v_cvt_pk_bf16_f32 v73, v22, v23
	ds_write_b64 v64, v[72:73]
	s_waitcnt lgkmcnt(0)
	s_barrier
	v_add3_u32 v72, s30, v51, v48
	s_waitcnt vmcnt(13)
	ds_write_b128 v72, v[200:203] offset:18432
	s_waitcnt vmcnt(12)
	ds_write_b128 v72, v[204:207] offset:27648
	s_waitcnt vmcnt(8)
	ds_write_b128 v72, v[208:211] offset:36864
	ds_write_b128 v72, v[44:47] offset:46080
	s_and_saveexec_b64 s[22:23], s[8:9]
	s_cbranch_execz .LBB0_437
	v_lshl_add_u32 v32, v134, 2, s30
	s_waitcnt vmcnt(7)
	ds_write_b128 v32, v[28:31] offset:55296
	s_branch .LBB0_437
